# Q up-projection phase offset retuned from 3 to 2 sleeps (about 4us)
# speedup vs baseline: 1.0065x; 1.0065x over previous
.LBB0_811:
	s_or_b64 exec, exec, s[0:1]
	v_mov_b32_e32 v8, v254
	s_waitcnt lgkmcnt(0)
	s_barrier
	s_bitcmp0_b32 s2, 3
	s_cbranch_scc1 .Lstg8_go
	s_sleep 64
	s_sleep 64
.Lstg8_go:
	s_cmpk_gt_i32 s2, 0x5ff
	v_readfirstlane_b32 s17, v8
	s_cbranch_scc1 .LBB0_825
	v_lshlrev_b32_e32 v0, 4, v8
	v_add_u32_e32 v1, 0x2000, v0
	v_ashrrev_i32_e32 v2, 31, v1
	v_lshrrev_b32_e32 v2, 22, v2
	v_add_u32_e32 v2, v1, v2
	v_ashrrev_i32_e32 v2, 10, v2
	v_mul_i32_i24_e32 v3, 0x400, v2
	v_sub_u32_e32 v1, v1, v3
	v_lshrrev_b32_e32 v3, 4, v1
	v_bitop3_b32 v1, v3, v1, 32 bitop3:0x6c
	v_ashrrev_i32_e32 v3, 31, v1
	v_lshrrev_b32_e32 v3, 26, v3
	v_add_u32_e32 v3, v1, v3
	v_lshlrev_b32_e32 v5, 3, v2
	v_ashrrev_i32_e32 v4, 6, v3
	v_and_b32_e32 v5, -16, v5
	v_and_b32_e32 v3, 0xc0, v3
	v_add_u32_e32 v5, v4, v5
	v_sub_u32_e32 v1, v1, v3
	v_mov_b32_e32 v3, 1
	v_and_b32_e32 v4, 3, v4
	s_mov_b32 s0, 0x7fffe0
	v_lshrrev_b32_e32 v6, 2, v5
	v_lshlrev_b32_e32 v7, 1, v5
	v_lshlrev_b32_e32 v2, 5, v2
	v_ashrrev_i16_sdwa v1, v3, sext(v1) dst_sel:DWORD dst_unused:UNUSED_PAD src0_sel:DWORD src1_sel:BYTE_0
	v_and_or_b32 v4, v5, s0, v4
	v_and_b32_e32 v6, 4, v6
	v_and_b32_e32 v7, 24, v7
	v_and_b32_e32 v2, 32, v2
	v_bfe_i32 v1, v1, 0, 16
	v_or3_b32 v4, v4, v6, v7
	v_add_lshl_u32 v1, v2, v1, 1
	v_lshl_add_u32 v160, v4, 9, v1
	v_lshl_add_u32 v162, v5, 9, v1
	v_bfe_i32 v1, v8, 27, 1
	v_lshrrev_b32_e32 v1, 22, v1
	v_add_u32_e32 v1, v0, v1
	v_and_b32_e32 v1, 0xfffffc00, v1
	v_sub_u32_e32 v0, v0, v1
	v_ashrrev_i32_e32 v2, 31, v8
	v_lshrrev_b32_e32 v1, 4, v0
	v_lshrrev_b32_e32 v2, 26, v2
	v_bitop3_b32 v1, v1, v0, 32 bitop3:0x6c
	v_ashrrev_i32_e32 v0, 31, v0
	v_add_u32_e32 v2, v8, v2
	v_lshrrev_b32_e32 v0, 26, v0
	v_ashrrev_i32_e32 v2, 6, v2
	v_add_u32_e32 v0, v1, v0
	v_lshlrev_b32_e32 v4, 3, v2
	s_add_u32 s72, s28, 0x17c00000
	v_ashrrev_i32_e32 v0, 6, v0
	v_and_b32_e32 v4, -16, v4
	s_addc_u32 s73, s29, 0
	v_add_u32_e32 v4, v0, v4
	v_and_b32_e32 v5, 3, v0
	s_ashr_i32 s3, s2, 31
	v_and_or_b32 v5, v4, s0, v5
	s_lshr_b32 s0, s3, 29
	s_add_i32 s0, s2, s0
	s_ashr_i32 s1, s17, 6
	s_ashr_i32 s7, s0, 3
	s_and_b32 s0, s0, -8
	s_ashr_i32 s6, s17, 8
	s_lshl_b32 s74, s1, 10
	s_sub_i32 s0, s2, s0
	s_cmp_lt_i32 s0, 0
	s_movk_i32 s75, 0xc1
	s_cselect_b32 s8, s75, 0xc0
	s_mul_i32 s0, s8, s0
	s_add_i32 s0, s0, s7
	s_mul_hi_i32 s7, s0, 0x2aaaaaab
	s_lshr_b32 s8, s7, 31
	s_ashr_i32 s7, s7, 4
	s_add_i32 s7, s7, s8
	s_lshl_b32 s8, s7, 3
	s_mulk_i32 s7, 0x60
	s_sub_i32 s7, s0, s7
	s_bfe_i32 s0, s7, 0x80000
	s_bfe_u32 s0, s0, 0x3000c
	s_add_i32 s9, s7, s0
	s_bfe_i32 s0, s9, 0x80000
	s_and_b32 s9, s9, 0xf8
	s_sub_i32 s7, s7, s9
	s_sext_i32_i16 s0, s0
	s_sext_i32_i8 s7, s7
	v_mul_i32_i24_e32 v0, 64, v0
	s_lshr_b32 s0, s0, 3
	s_add_i32 s62, s8, s7
	v_sub_u32_e32 v0, v1, v0
	s_ashr_i32 s63, s62, 31
	s_bfe_i64 s[12:13], s[0:1], 0x100000
	v_lshrrev_b32_e32 v6, 2, v4
	v_lshlrev_b32_e32 v7, 1, v4
	v_lshlrev_b32_e32 v2, 5, v2
	v_ashrrev_i16_sdwa v0, v3, sext(v0) dst_sel:DWORD dst_unused:UNUSED_PAD src0_sel:DWORD src1_sel:BYTE_0
	s_lshl_b64 s[8:9], s[62:63], 17
	s_lshl_b64 s[12:13], s[12:13], 17
	v_and_b32_e32 v6, 4, v6
	v_and_b32_e32 v7, 24, v7
	v_and_b32_e32 v2, 32, v2
	v_bfe_i32 v0, v0, 0, 16
	s_add_u32 s66, s68, s12
	v_or3_b32 v5, v5, v6, v7
	v_add_lshl_u32 v0, v2, v0, 1
	s_addc_u32 s67, s69, s13
	s_add_i32 s63, s74, 0
	v_lshl_add_u32 v164, v5, 9, v0
	s_add_i32 m0, s63, 0x10000
	v_lshl_add_u32 v166, v4, 9, v0
	global_load_lds_dwordx4 v164, s[66:67]
	s_add_i32 m0, s63, 0x12000
	s_add_u32 s64, s72, s8
	global_load_lds_dwordx4 v160, s[66:67]
	s_addc_u32 s65, s73, s9
	s_mov_b32 m0, s63
	s_add_i32 s76, s63, 0x2000
	global_load_lds_dwordx4 v166, s[64:65]
	s_mov_b32 m0, s76
	s_add_u32 s8, s66, 0x10000
	global_load_lds_dwordx4 v162, s[64:65]
	s_addc_u32 s9, s67, 0
	s_add_i32 m0, s63, 0x14000
	v_mov_b32_e32 v169, 0
	global_load_lds_dwordx4 v164, s[8:9]
	s_add_i32 m0, s63, 0x16000
	v_mov_b32_e32 v165, v169
	global_load_lds_dwordx4 v160, s[8:9]
	s_add_u32 s8, s64, 0x10000
	s_addc_u32 s9, s65, 0
	s_add_i32 s77, s63, 0x4000
	s_mov_b32 m0, s77
	s_add_i32 s78, s63, 0x6000
	global_load_lds_dwordx4 v166, s[8:9]
	s_mov_b32 m0, s78
	v_mov_b32_e32 v161, v169
	global_load_lds_dwordx4 v162, s[8:9]
	v_mov_b32_e32 v167, v169
	v_mov_b32_e32 v163, v169
	s_movk_i32 s79, 0x2000
	s_movk_i32 s80, 0xf8
	v_lshl_add_u64 v[6:7], s[66:67], 0, v[164:165]
	v_lshl_add_u64 v[4:5], s[66:67], 0, v[160:161]
	v_lshl_add_u64 v[2:3], s[64:65], 0, v[166:167]
	s_cmp_lg_u32 s6, 1
	v_lshl_add_u64 v[0:1], s[64:65], 0, v[162:163]
	s_cbranch_scc1 .LBB0_814
	s_barrier
